# sample_attn: sinks loaded once with the K/V burst, q wait moved behind load issue, wave_sum/wave_max via DPP + permlane swaps
# speedup vs baseline: 1.0104x; 1.0019x over previous
.LBB0_827:
	s_ashr_i32 s14, s30, 2
	s_and_b32 s19, s30, 3
	s_lshl_b32 s18, s19, 2
	s_ashr_i32 s15, s14, 31
	s_or_b32 s52, s18, s25
	s_lshl_b64 s[16:17], s[14:15], 12
	s_add_u32 s16, s23, s16
	s_addc_u32 s17, s24, s17
	s_lshl_b32 s52, s52, 8
	s_add_u32 s16, s16, s52
	s_addc_u32 s17, s17, 0
	s_barrier
	global_load_dword v124, v194, s[16:17]
	s_lshl_b32 s98, s18, 2
	s_add_u32 s98, s12, s98
	s_addc_u32 s99, s13, 0
	global_load_dwordx4 v[126:129], v195, s[98:99]
	s_lshl_b32 s16, s14, 7
	s_lshl_b32 s94, s19, 8
	v_mov_b32_e32 v37, v195
	s_or_b32 s52, s16, s26
	s_ashr_i32 s53, s52, 31
	s_lshl_b64 s[52:53], s[52:53], 10
	s_add_u32 s17, s20, s52
	s_addc_u32 s19, s3, s53
	s_add_u32 s52, s17, s94
	s_addc_u32 s53, s19, 0
	v_lshl_add_u64 v[38:39], s[52:53], 0, v[194:195]
	s_movk_i32 s17, 0x1000
	v_add_co_u32_e32 v72, vcc, s17, v38
	s_movk_i32 s17, 0x2000
	s_nop 0
	v_addc_co_u32_e32 v73, vcc, 0, v39, vcc
	v_add_co_u32_e32 v80, vcc, s17, v38
	s_movk_i32 s17, 0x3000
	s_nop 0
	v_addc_co_u32_e32 v81, vcc, 0, v39, vcc
	v_or_b32_e32 v2, s16, v41
	v_ashrrev_i32_e32 v3, 31, v2
	v_lshlrev_b64 v[2:3], 10, v[2:3]
	v_lshl_add_u64 v[2:3], s[10:11], 0, v[2:3]
	v_lshl_add_u64 v[2:3], v[2:3], 0, s[94:95]
	v_lshl_add_u64 v[14:15], v[2:3], 0, v[36:37]
	global_load_dwordx4 v[18:21], v[14:15], off offset:48
	global_load_dwordx4 v[22:25], v[14:15], off offset:32
	global_load_dwordx4 v[26:29], v[14:15], off offset:16
	global_load_dwordx4 v[30:33], v[14:15], off
	global_load_dwordx4 v[2:5], v[14:15], off offset:112
	global_load_dwordx4 v[6:9], v[14:15], off offset:96
	global_load_dwordx4 v[10:13], v[14:15], off offset:80
	s_nop 0
	global_load_dwordx4 v[14:17], v[14:15], off offset:64
	s_nop 0
	global_load_dword v70, v194, s[52:53]
	global_load_dword v69, v194, s[52:53] offset:1024
	global_load_dword v68, v194, s[52:53] offset:2048
	global_load_dword v37, v194, s[52:53] offset:3072
	global_load_dword v78, v[80:81], off offset:-4096
	global_load_dword v77, v[72:73], off offset:1024
	global_load_dword v76, v[72:73], off offset:2048
	global_load_dword v75, v[72:73], off offset:3072
	global_load_dword v74, v[80:81], off
	s_nop 0
	global_load_dword v73, v[80:81], off offset:1024
	global_load_dword v72, v[80:81], off offset:2048
	global_load_dword v71, v[80:81], off offset:3072
	v_add_co_u32_e32 v80, vcc, s17, v38
	s_movk_i32 s17, 0x4000
	s_nop 0
	v_addc_co_u32_e32 v81, vcc, 0, v39, vcc
	v_add_co_u32_e32 v88, vcc, s17, v38
	s_movk_i32 s17, 0x5000
	s_nop 0
	v_addc_co_u32_e32 v89, vcc, 0, v39, vcc
	global_load_dword v86, v[88:89], off offset:-4096
	global_load_dword v83, v[80:81], off offset:1024
	global_load_dword v84, v[80:81], off offset:2048
	global_load_dword v85, v[80:81], off offset:3072
	global_load_dword v79, v[88:89], off
	s_nop 0
	global_load_dword v80, v[88:89], off offset:1024
	global_load_dword v81, v[88:89], off offset:2048
	global_load_dword v82, v[88:89], off offset:3072
	v_add_co_u32_e32 v88, vcc, s17, v38
	s_movk_i32 s17, 0x6000
	s_nop 0
	v_addc_co_u32_e32 v89, vcc, 0, v39, vcc
	v_add_co_u32_e32 v92, vcc, s17, v38
	s_movk_i32 s17, 0x7000
	s_nop 0
	v_addc_co_u32_e32 v93, vcc, 0, v39, vcc
	s_or_b32 s16, s16, 0x7f
	v_add_co_u32_e32 v98, vcc, s17, v38
	s_ashr_i32 s17, s16, 31
	s_lshl_b64 s[16:17], s[16:17], 10
	s_add_u32 s16, s22, s16
	s_addc_u32 s17, s21, s17
	s_add_u32 s16, s16, s94
	s_addc_u32 s17, s17, 0
	v_addc_co_u32_e32 v99, vcc, 0, v39, vcc
	v_lshl_add_u64 v[100:101], s[16:17], 0, v[194:195]
	s_mov_b32 s16, 0x49c0000
	global_load_dword v87, v[92:93], off offset:-4096
	global_load_dword v94, v[88:89], off offset:1024
	global_load_dword v95, v[88:89], off offset:2048
	global_load_dword v96, v[88:89], off offset:3072
	s_nop 0
	global_load_dword v89, v[92:93], off
	global_load_dword v90, v[92:93], off offset:1024
	global_load_dword v91, v[92:93], off offset:2048
	s_nop 0
	global_load_dword v92, v[92:93], off offset:3072
	s_nop 0
	global_load_dword v93, v[98:99], off
	global_load_dword v38, v[98:99], off offset:1024
	global_load_dword v39, v[98:99], off offset:2048
	global_load_dword v88, v[98:99], off offset:3072
	v_add_co_u32_e32 v98, vcc, s16, v100
	s_mov_b32 s16, 0x59c0000
	s_nop 0
	v_addc_co_u32_e32 v99, vcc, 0, v101, vcc
	global_load_dword v98, v[98:99], off
	v_add_co_u32_e32 v100, vcc, s16, v100
	s_nop 1
	v_addc_co_u32_e32 v101, vcc, 0, v101, vcc
	global_load_dword v97, v[100:101], off
	s_waitcnt vmcnt(43)
	ds_write_b32 v40, v124
	s_waitcnt lgkmcnt(0)
	s_barrier
	ds_read_b128 v[100:103], v42
	ds_read_b128 v[104:107], v42 offset:16
	ds_read_b128 v[108:111], v42 offset:32
	ds_read_b128 v[112:115], v42 offset:48
	s_waitcnt vmcnt(38) lgkmcnt(3)
	v_mul_f32_e32 v99, v31, v101
	v_fmac_f32_e32 v99, v30, v100
	v_mul_f32_e32 v100, v33, v103
	v_fmac_f32_e32 v100, v32, v102
	v_add_f32_e32 v99, v99, v100
	s_waitcnt lgkmcnt(2)
	v_mul_f32_e32 v100, v27, v105
	v_mul_f32_e32 v101, v29, v107
	v_fmac_f32_e32 v100, v26, v104
	v_fmac_f32_e32 v101, v28, v106
	v_add_f32_e32 v99, 0, v99
	v_add_f32_e32 v100, v100, v101
	v_add_f32_e32 v99, v99, v100
	s_waitcnt lgkmcnt(1)
	v_mul_f32_e32 v100, v23, v109
	v_mul_f32_e32 v101, v25, v111
	v_fmac_f32_e32 v100, v22, v108
	v_fmac_f32_e32 v101, v24, v110
	v_add_f32_e32 v100, v100, v101
	v_add_f32_e32 v99, v99, v100
	s_waitcnt lgkmcnt(0)
	v_mul_f32_e32 v100, v19, v113
	v_mul_f32_e32 v101, v21, v115
	v_fmac_f32_e32 v100, v18, v112
	v_fmac_f32_e32 v101, v20, v114
	v_add_f32_e32 v100, v100, v101
	v_add_f32_e32 v99, v99, v100
	ds_read_b128 v[100:103], v42 offset:64
	s_waitcnt vmcnt(34) lgkmcnt(0)
	v_mul_f32_e32 v101, v15, v101
	v_fmac_f32_e32 v101, v14, v100
	v_mul_f32_e32 v100, v17, v103
	v_fmac_f32_e32 v100, v16, v102
	v_add_f32_e32 v100, v101, v100
	v_add_f32_e32 v99, v99, v100
	ds_read_b128 v[100:103], v42 offset:80
	s_waitcnt lgkmcnt(0)
	v_mul_f32_e32 v101, v11, v101
	v_fmac_f32_e32 v101, v10, v100
	v_mul_f32_e32 v100, v13, v103
	v_fmac_f32_e32 v100, v12, v102
	v_add_f32_e32 v100, v101, v100
	v_add_f32_e32 v99, v99, v100
	ds_read_b128 v[100:103], v42 offset:96
	s_waitcnt lgkmcnt(0)
	v_mul_f32_e32 v101, v7, v101
	v_fmac_f32_e32 v101, v6, v100
	v_mul_f32_e32 v100, v9, v103
	v_fmac_f32_e32 v100, v8, v102
	v_add_f32_e32 v100, v101, v100
	v_add_f32_e32 v99, v99, v100
	ds_read_b128 v[100:103], v42 offset:112
	s_waitcnt lgkmcnt(0)
	v_mul_f32_e32 v101, v3, v101
	v_fmac_f32_e32 v101, v2, v100
	v_mul_f32_e32 v100, v5, v103
	v_fmac_f32_e32 v100, v4, v102
	v_add_f32_e32 v100, v101, v100
	v_add_f32_e32 v99, v99, v100
	v_mov_b32_e32 v100, v99
	v_mov_b32_e32 v130, v99
	s_nop 1
	v_permlane32_swap_b32 v100, v130
	v_add_f32_e32 v99, v100, v130
	v_mul_f32_e32 v99, 0x3e000000, v99
	v_cndmask_b32_e64 v99, v99, v245, s[0:1]
	ds_read_b32 v100, v44
	s_waitcnt vmcnt(1) lgkmcnt(0)
	v_mul_f32_e32 v101, v98, v100
	s_nop 1
	v_max_f32_dpp v102, v99, v99 quad_perm:[1,0,3,2] row_mask:0xf bank_mask:0xf
	s_nop 1
	v_add_f32_dpp v101, v101, v101 quad_perm:[1,0,3,2] row_mask:0xf bank_mask:0xf
	s_nop 1
	v_max_f32_dpp v102, v102, v102 quad_perm:[2,3,0,1] row_mask:0xf bank_mask:0xf
	s_nop 1
	v_add_f32_dpp v100, v101, v101 quad_perm:[2,3,0,1] row_mask:0xf bank_mask:0xf
	s_nop 1
	v_max_f32_dpp v102, v102, v102 row_half_mirror row_mask:0xf bank_mask:0xf
	s_nop 1
	v_add_f32_dpp v100, v100, v100 row_half_mirror row_mask:0xf bank_mask:0xf
	s_nop 1
	v_max_f32_dpp v102, v102, v102 row_mirror row_mask:0xf bank_mask:0xf
	s_nop 1
	v_add_f32_dpp v100, v100, v100 row_mirror row_mask:0xf bank_mask:0xf
	v_mov_b32_e32 v101, v100
	v_mov_b32_e32 v130, v100
	s_nop 1
	v_permlane16_swap_b32 v101, v130
	v_add_f32_e32 v100, v101, v130
	v_mov_b32_e32 v103, v102
	v_mov_b32_e32 v130, v102
	s_nop 1
	v_permlane16_swap_b32 v103, v130
	v_max_f32_e32 v102, v103, v130
	v_mov_b32_e32 v103, v102
	v_mov_b32_e32 v130, v102
	s_nop 1
	v_permlane32_swap_b32 v130, v103
	s_and_saveexec_b64 s[16:17], s[4:5]
	s_cbranch_execz .LBB0_829
	v_max_f32_e32 v103, v103, v103
	v_max_f32_e32 v102, v102, v102
	s_add_i32 s19, s27, 0
	v_max_f32_e32 v102, v102, v103
	v_mov_b32_e32 v103, s19
	ds_write_b32 v103, v102 offset:2048
.LBB0_829:
	s_or_b64 exec, exec, s[16:17]
	s_waitcnt lgkmcnt(0)
	ds_read_b128 v[102:105], v42 offset:256
	ds_read_b128 v[106:109], v42 offset:272
	ds_read_b128 v[110:113], v42 offset:288
	ds_read_b128 v[114:117], v42 offset:304
	s_waitcnt lgkmcnt(3)
	v_mul_f32_e32 v103, v31, v103
	v_mul_f32_e32 v105, v33, v105
	v_fmac_f32_e32 v103, v30, v102
	v_fmac_f32_e32 v105, v32, v104
	v_add_f32_e32 v102, v103, v105
	s_waitcnt lgkmcnt(2)
	v_mul_f32_e32 v103, v27, v107
	v_mul_f32_e32 v104, v29, v109
	v_fmac_f32_e32 v103, v26, v106
	v_fmac_f32_e32 v104, v28, v108
	v_add_f32_e32 v102, 0, v102
	v_add_f32_e32 v103, v103, v104
	v_add_f32_e32 v102, v102, v103
	s_waitcnt lgkmcnt(1)
	v_mul_f32_e32 v103, v23, v111
	v_mul_f32_e32 v104, v25, v113
	v_fmac_f32_e32 v103, v22, v110
	v_fmac_f32_e32 v104, v24, v112
	v_add_f32_e32 v103, v103, v104
	v_add_f32_e32 v106, v102, v103
	s_waitcnt lgkmcnt(0)
	v_mul_f32_e32 v107, v19, v115
	v_mul_f32_e32 v108, v21, v117
	ds_read_b128 v[102:105], v42 offset:320
	v_fmac_f32_e32 v107, v18, v114
	v_fmac_f32_e32 v108, v20, v116
	v_add_f32_e32 v107, v107, v108
	v_add_f32_e32 v110, v106, v107
	ds_read_b128 v[106:109], v42 offset:336
	s_waitcnt lgkmcnt(1)
	v_mul_f32_e32 v103, v15, v103
	v_fmac_f32_e32 v103, v14, v102
	v_mul_f32_e32 v102, v17, v105
	v_fmac_f32_e32 v102, v16, v104
	v_add_f32_e32 v102, v103, v102
	s_waitcnt lgkmcnt(0)
	v_mul_f32_e32 v107, v11, v107
	v_add_f32_e32 v110, v110, v102
	v_fmac_f32_e32 v107, v10, v106
	v_mul_f32_e32 v106, v13, v109
	ds_read_b128 v[102:105], v42 offset:352
	v_fmac_f32_e32 v106, v12, v108
	v_add_f32_e32 v106, v107, v106
	v_add_f32_e32 v110, v110, v106
	ds_read_b128 v[106:109], v42 offset:368
	s_waitcnt lgkmcnt(1)
	v_mul_f32_e32 v103, v7, v103
	v_fmac_f32_e32 v103, v6, v102
	v_mul_f32_e32 v102, v9, v105
	v_fmac_f32_e32 v102, v8, v104
	v_add_f32_e32 v102, v103, v102
	s_waitcnt lgkmcnt(0)
	v_mul_f32_e32 v103, v3, v107
	v_mul_f32_e32 v104, v5, v109
	v_fmac_f32_e32 v103, v2, v106
	v_fmac_f32_e32 v104, v4, v108
	v_add_f32_e32 v102, v110, v102
	v_add_f32_e32 v103, v103, v104
	v_add_f32_e32 v102, v102, v103
	ds_read_b32 v104, v44 offset:256
	v_mov_b32_e32 v103, v102
	v_mov_b32_e32 v130, v102
	s_nop 1
	v_permlane32_swap_b32 v103, v130
	v_add_f32_e32 v102, v103, v130
	v_mul_f32_e32 v102, 0x3e000000, v102
	v_cndmask_b32_e64 v102, v102, v245, s[0:1]
	s_waitcnt lgkmcnt(0)
	v_mul_f32_e32 v103, v98, v104
	s_nop 1
	v_max_f32_dpp v105, v102, v102 quad_perm:[1,0,3,2] row_mask:0xf bank_mask:0xf
	s_nop 1
	v_add_f32_dpp v103, v103, v103 quad_perm:[1,0,3,2] row_mask:0xf bank_mask:0xf
	s_nop 1
	v_max_f32_dpp v105, v105, v105 quad_perm:[2,3,0,1] row_mask:0xf bank_mask:0xf
	s_nop 1
	v_add_f32_dpp v103, v103, v103 quad_perm:[2,3,0,1] row_mask:0xf bank_mask:0xf
	s_nop 1
	v_max_f32_dpp v105, v105, v105 row_half_mirror row_mask:0xf bank_mask:0xf
	s_nop 1
	v_add_f32_dpp v103, v103, v103 row_half_mirror row_mask:0xf bank_mask:0xf
	s_nop 1
	v_add_f32_dpp v103, v103, v103 row_mirror row_mask:0xf bank_mask:0xf
	s_nop 1
	v_max_f32_dpp v106, v105, v105 row_mirror row_mask:0xf bank_mask:0xf
	v_mov_b32_e32 v104, v103
	v_mov_b32_e32 v130, v103
	s_nop 1
	v_permlane16_swap_b32 v104, v130
	v_add_f32_e32 v104, v104, v130
	v_mov_b32_e32 v107, v106
	v_mov_b32_e32 v130, v106
	s_nop 1
	v_permlane16_swap_b32 v107, v130
	v_max_f32_e32 v103, v107, v130
	v_mov_b32_e32 v106, v103
	v_mov_b32_e32 v130, v103
	s_nop 1
	v_permlane32_swap_b32 v130, v106
	s_and_saveexec_b64 s[16:17], s[4:5]
	s_cbranch_execz .LBB0_831
	v_max_f32_e32 v106, v106, v106
	v_max_f32_e32 v103, v103, v103
	s_add_i32 s19, s27, 0
	v_max_f32_e32 v103, v103, v106
	v_mov_b32_e32 v106, s19
	ds_write_b32 v106, v103 offset:2056
.LBB0_831:
	s_or_b64 exec, exec, s[16:17]
	s_waitcnt lgkmcnt(0)
	ds_read_b128 v[106:109], v42 offset:512
	ds_read_b128 v[110:113], v42 offset:528
	ds_read_b128 v[114:117], v42 offset:544
	ds_read_b128 v[118:121], v42 offset:560
	s_waitcnt lgkmcnt(3)
	v_mul_f32_e32 v103, v31, v107
	v_mul_f32_e32 v107, v33, v109
	v_fmac_f32_e32 v103, v30, v106
	v_fmac_f32_e32 v107, v32, v108
	v_add_f32_e32 v103, v103, v107
	s_waitcnt lgkmcnt(2)
	v_mul_f32_e32 v106, v27, v111
	v_mul_f32_e32 v107, v29, v113
	v_fmac_f32_e32 v106, v26, v110
	v_fmac_f32_e32 v107, v28, v112
	v_add_f32_e32 v103, 0, v103
	v_add_f32_e32 v106, v106, v107
	v_add_f32_e32 v103, v103, v106
	s_waitcnt lgkmcnt(1)
	v_mul_f32_e32 v106, v23, v115
	v_mul_f32_e32 v107, v25, v117
	v_fmac_f32_e32 v106, v22, v114
	v_fmac_f32_e32 v107, v24, v116
	v_add_f32_e32 v106, v106, v107
	v_add_f32_e32 v103, v103, v106
	ds_read_b128 v[106:109], v42 offset:576
	s_waitcnt lgkmcnt(1)
	v_mul_f32_e32 v110, v19, v119
	v_mul_f32_e32 v111, v21, v121
	v_fmac_f32_e32 v110, v18, v118
	v_fmac_f32_e32 v111, v20, v120
	v_add_f32_e32 v110, v110, v111
	v_add_f32_e32 v103, v103, v110
	ds_read_b128 v[110:113], v42 offset:592
	s_waitcnt lgkmcnt(1)
	v_mul_f32_e32 v107, v15, v107
	v_fmac_f32_e32 v107, v14, v106
	v_mul_f32_e32 v106, v17, v109
	v_fmac_f32_e32 v106, v16, v108
	v_add_f32_e32 v106, v107, v106
	v_add_f32_e32 v103, v103, v106
	s_waitcnt lgkmcnt(0)
	v_mul_f32_e32 v111, v11, v111
	ds_read_b128 v[106:109], v42 offset:608
	v_fmac_f32_e32 v111, v10, v110
	v_mul_f32_e32 v110, v13, v113
	v_fmac_f32_e32 v110, v12, v112
	v_add_f32_e32 v110, v111, v110
	v_add_f32_e32 v103, v103, v110
	ds_read_b128 v[110:113], v42 offset:624
	s_waitcnt lgkmcnt(1)
	v_mul_f32_e32 v107, v7, v107
	v_fmac_f32_e32 v107, v6, v106
	v_mul_f32_e32 v106, v9, v109
	v_fmac_f32_e32 v106, v8, v108
	v_add_f32_e32 v106, v107, v106
	v_add_f32_e32 v103, v103, v106
	s_waitcnt lgkmcnt(0)
	v_mul_f32_e32 v106, v3, v111
	v_mul_f32_e32 v107, v5, v113
	v_fmac_f32_e32 v106, v2, v110
	v_fmac_f32_e32 v107, v4, v112
	v_add_f32_e32 v106, v106, v107
	v_add_f32_e32 v103, v103, v106
	ds_read_b32 v107, v44 offset:512
	v_mov_b32_e32 v106, v103
	v_mov_b32_e32 v130, v103
	s_nop 1
	v_permlane32_swap_b32 v106, v130
	v_add_f32_e32 v103, v106, v130
	v_mul_f32_e32 v103, 0x3e000000, v103
	v_cndmask_b32_e64 v103, v103, v245, s[0:1]
	s_waitcnt lgkmcnt(0)
	v_mul_f32_e32 v106, v98, v107
	s_nop 1
	v_max_f32_dpp v108, v103, v103 quad_perm:[1,0,3,2] row_mask:0xf bank_mask:0xf
	s_nop 1
	v_add_f32_dpp v106, v106, v106 quad_perm:[1,0,3,2] row_mask:0xf bank_mask:0xf
	s_nop 1
	v_max_f32_dpp v108, v108, v108 quad_perm:[2,3,0,1] row_mask:0xf bank_mask:0xf
	s_nop 1
	v_add_f32_dpp v106, v106, v106 quad_perm:[2,3,0,1] row_mask:0xf bank_mask:0xf
	s_nop 1
	v_max_f32_dpp v108, v108, v108 row_half_mirror row_mask:0xf bank_mask:0xf
	s_nop 1
	v_add_f32_dpp v106, v106, v106 row_half_mirror row_mask:0xf bank_mask:0xf
	s_nop 1
	v_max_f32_dpp v108, v108, v108 row_mirror row_mask:0xf bank_mask:0xf
	s_nop 1
	v_add_f32_dpp v106, v106, v106 row_mirror row_mask:0xf bank_mask:0xf
	v_mov_b32_e32 v107, v106
	v_mov_b32_e32 v130, v106
	s_nop 1
	v_permlane16_swap_b32 v107, v130
	v_add_f32_e32 v106, v107, v130
	v_mov_b32_e32 v109, v108
	v_mov_b32_e32 v130, v108
	s_nop 1
	v_permlane16_swap_b32 v109, v130
	v_max_f32_e32 v108, v109, v130
	v_mov_b32_e32 v109, v108
	v_mov_b32_e32 v130, v108
	s_nop 1
	v_permlane32_swap_b32 v130, v109
	s_and_saveexec_b64 s[16:17], s[4:5]
	s_cbranch_execz .LBB0_833
	v_max_f32_e32 v109, v109, v109
	v_max_f32_e32 v108, v108, v108
	s_add_i32 s19, s27, 0
	v_max_f32_e32 v108, v108, v109
	v_mov_b32_e32 v109, s19
	ds_write_b32 v109, v108 offset:2064
.LBB0_833:
	s_or_b64 exec, exec, s[16:17]
	s_waitcnt lgkmcnt(0)
	ds_read_b128 v[108:111], v42 offset:768
	ds_read_b128 v[112:115], v42 offset:784
	ds_read_b128 v[116:119], v42 offset:800
	ds_read_b128 v[120:123], v42 offset:816
	s_waitcnt lgkmcnt(3)
	v_mul_f32_e32 v31, v31, v109
	v_mul_f32_e32 v33, v33, v111
	s_waitcnt lgkmcnt(2)
	v_mul_f32_e32 v27, v27, v113
	v_fmac_f32_e32 v31, v30, v108
	v_fmac_f32_e32 v33, v32, v110
	v_fmac_f32_e32 v27, v26, v112
	v_mul_f32_e32 v26, v29, v115
	s_waitcnt lgkmcnt(1)
	v_mul_f32_e32 v23, v23, v117
	v_add_f32_e32 v30, v31, v33
	v_fmac_f32_e32 v26, v28, v114
	v_fmac_f32_e32 v23, v22, v116
	v_mul_f32_e32 v22, v25, v119
	s_waitcnt lgkmcnt(0)
	v_mul_f32_e32 v19, v19, v121
	v_add_f32_e32 v30, 0, v30
	v_add_f32_e32 v26, v27, v26
	v_fmac_f32_e32 v22, v24, v118
	v_fmac_f32_e32 v19, v18, v120
	v_mul_f32_e32 v18, v21, v123
	v_add_f32_e32 v26, v30, v26
	v_add_f32_e32 v22, v23, v22
	v_fmac_f32_e32 v18, v20, v122
	v_add_f32_e32 v26, v26, v22
	ds_read_b128 v[22:25], v42 offset:832
	v_add_f32_e32 v18, v19, v18
	v_add_f32_e32 v26, v26, v18
	ds_read_b128 v[18:21], v42 offset:848
	s_waitcnt lgkmcnt(1)
	v_mul_f32_e32 v15, v15, v23
	v_fmac_f32_e32 v15, v14, v22
	v_mul_f32_e32 v14, v17, v25
	s_waitcnt lgkmcnt(0)
	v_mul_f32_e32 v11, v11, v19
	v_fmac_f32_e32 v14, v16, v24
	v_fmac_f32_e32 v11, v10, v18
	v_mul_f32_e32 v10, v13, v21
	v_add_f32_e32 v14, v15, v14
	v_fmac_f32_e32 v10, v12, v20
	v_add_f32_e32 v22, v26, v14
	ds_read_b128 v[14:17], v42 offset:864
	v_add_f32_e32 v10, v11, v10
	v_add_f32_e32 v18, v22, v10
	ds_read_b128 v[10:13], v42 offset:880
	s_waitcnt lgkmcnt(1)
	v_mul_f32_e32 v7, v7, v15
	v_fmac_f32_e32 v7, v6, v14
	v_mul_f32_e32 v6, v9, v17
	s_waitcnt lgkmcnt(0)
	v_mul_f32_e32 v3, v3, v11
	v_fmac_f32_e32 v6, v8, v16
	v_fmac_f32_e32 v3, v2, v10
	v_mul_f32_e32 v2, v5, v13
	v_add_f32_e32 v6, v7, v6
	v_fmac_f32_e32 v2, v4, v12
	v_add_f32_e32 v6, v18, v6
	v_add_f32_e32 v2, v3, v2
	v_add_f32_e32 v2, v6, v2
	ds_read_b32 v4, v44 offset:768
	v_mov_b32_e32 v3, v2
	v_mov_b32_e32 v130, v2
	s_nop 1
	v_permlane32_swap_b32 v3, v130
	v_add_f32_e32 v2, v3, v130
	v_mul_f32_e32 v2, 0x3e000000, v2
	v_cndmask_b32_e64 v9, v2, v245, s[0:1]
	s_waitcnt lgkmcnt(0)
	v_mul_f32_e32 v3, v98, v4
	s_nop 1
	v_max_f32_dpp v2, v9, v9 quad_perm:[1,0,3,2] row_mask:0xf bank_mask:0xf
	s_nop 1
	v_add_f32_dpp v3, v3, v3 quad_perm:[1,0,3,2] row_mask:0xf bank_mask:0xf
	s_nop 1
	v_max_f32_dpp v2, v2, v2 quad_perm:[2,3,0,1] row_mask:0xf bank_mask:0xf
	s_nop 1
	v_add_f32_dpp v3, v3, v3 quad_perm:[2,3,0,1] row_mask:0xf bank_mask:0xf
	s_nop 1
	v_max_f32_dpp v2, v2, v2 row_half_mirror row_mask:0xf bank_mask:0xf
	s_nop 1
	v_add_f32_dpp v3, v3, v3 row_half_mirror row_mask:0xf bank_mask:0xf
	s_nop 1
	v_max_f32_dpp v2, v2, v2 row_mirror row_mask:0xf bank_mask:0xf
	s_nop 1
	v_add_f32_dpp v3, v3, v3 row_mirror row_mask:0xf bank_mask:0xf
	v_mov_b32_e32 v4, v3
	v_mov_b32_e32 v130, v3
	s_nop 1
	v_permlane16_swap_b32 v4, v130
	v_add_f32_e32 v3, v4, v130
	v_mov_b32_e32 v5, v2
	v_mov_b32_e32 v130, v2
	s_nop 1
	v_permlane16_swap_b32 v5, v130
	v_max_f32_e32 v2, v5, v130
	v_mov_b32_e32 v5, v2
	v_mov_b32_e32 v130, v2
	s_nop 1
	v_permlane32_swap_b32 v130, v5
	s_and_saveexec_b64 s[16:17], s[4:5]
	s_cbranch_execz .LBB0_835
	v_max_f32_e32 v5, v5, v5
	v_max_f32_e32 v2, v2, v2
	s_add_i32 s19, s27, 0
	v_max_f32_e32 v2, v2, v5
	v_mov_b32_e32 v5, s19
	ds_write_b32 v5, v2 offset:2072
.LBB0_835:
	s_or_b64 exec, exec, s[16:17]
	s_lshl_b32 s16, s18, 2
	v_mov_b32_e32 v2, s16
	s_waitcnt lgkmcnt(0)
	s_barrier
	v_mov_b32_e32 v2, v126
	v_mov_b32_e32 v6, s50
	v_add_u32_e32 v7, 0x800, v6
	ds_read2_b32 v[10:11], v7 offset1:8
	v_mov_b32_e32 v7, s51
	ds_read_b32 v6, v6 offset:2112
	ds_read_b32 v8, v7 offset:2048
	v_mov_b32_e32 v101, v100
	v_mov_b32_e32 v130, v100
	s_nop 1
	v_permlane32_swap_b32 v101, v130
	v_add_f32_e32 v5, v101, v130
	v_mul_f32_e32 v7, 0x3e000000, v5
	s_add_u32 s16, s12, s16
	s_addc_u32 s17, s13, 0
	s_waitcnt vmcnt(0)
	v_max_f32_e32 v2, v2, v2
	v_max_f32_e32 v2, v7, v2
	s_waitcnt lgkmcnt(2)
	v_max3_f32 v2, v2, v10, v11
	s_waitcnt lgkmcnt(0)
	v_max3_f32 v8, v2, v6, v8
	v_sub_f32_e32 v2, v99, v8
	v_mul_f32_e32 v2, 0x3fb8aa3b, v2
	v_exp_f32_e32 v2, v2
	s_nop 1
	v_add_f32_dpp v5, v2, v2 quad_perm:[1,0,3,2] row_mask:0xf bank_mask:0xf
	s_nop 1
	v_add_f32_dpp v5, v5, v5 quad_perm:[2,3,0,1] row_mask:0xf bank_mask:0xf
	s_nop 1
	v_add_f32_dpp v5, v5, v5 row_half_mirror row_mask:0xf bank_mask:0xf
	s_nop 1
	v_add_f32_dpp v5, v5, v5 row_mirror row_mask:0xf bank_mask:0xf
	v_mov_b32_e32 v6, v5
	v_mov_b32_e32 v130, v5
	s_nop 1
	v_permlane16_swap_b32 v6, v130
	v_add_f32_e32 v5, v6, v130
	v_mov_b32_e32 v6, v5
	v_mov_b32_e32 v130, v5
	s_nop 1
	v_permlane32_swap_b32 v130, v6
	s_and_saveexec_b64 s[18:19], s[4:5]
	s_cbranch_execz .LBB0_837
	v_add_f32_e32 v5, v5, v6
	s_add_i32 s52, s27, 0
	v_mul_f32_e32 v5, 0.5, v5
	v_mov_b32_e32 v6, s52
	ds_write_b32 v6, v5 offset:2052
.LBB0_837:
	s_or_b64 exec, exec, s[18:19]
	s_and_saveexec_b64 s[18:19], s[6:7]
	ds_write_b32 v50, v2 offset:2560
	s_or_b64 exec, exec, s[18:19]
	v_mov_b32_e32 v5, v127
	s_waitcnt lgkmcnt(0)
	v_mov_b32_e32 v6, s50
	v_add_u32_e32 v10, 0x800, v6
	ds_read2_b32 v[10:11], v10 offset0:2 offset1:10
	v_mov_b32_e32 v105, v104
	v_mov_b32_e32 v130, v104
	s_nop 1
	v_permlane32_swap_b32 v105, v130
	v_add_f32_e32 v2, v105, v130
	v_mul_f32_e32 v2, 0x3e000000, v2
	ds_read_b32 v6, v6 offset:2120
	s_waitcnt vmcnt(0)
	v_max_f32_e32 v5, v5, v5
	v_max_f32_e32 v5, v2, v5
	s_waitcnt lgkmcnt(1)
	v_max3_f32 v5, v5, v10, v11
	v_mov_b32_e32 v10, s51
	ds_read_b32 v10, v10 offset:2056
	s_waitcnt lgkmcnt(0)
	v_max3_f32 v6, v5, v6, v10
	v_sub_f32_e32 v5, v102, v6
	v_mul_f32_e32 v5, 0x3fb8aa3b, v5
	v_exp_f32_e32 v5, v5
	s_nop 1
	v_add_f32_dpp v10, v5, v5 quad_perm:[1,0,3,2] row_mask:0xf bank_mask:0xf
	s_nop 1
	v_add_f32_dpp v10, v10, v10 quad_perm:[2,3,0,1] row_mask:0xf bank_mask:0xf
	s_nop 1
	v_add_f32_dpp v10, v10, v10 row_half_mirror row_mask:0xf bank_mask:0xf
	s_nop 1
	v_add_f32_dpp v10, v10, v10 row_mirror row_mask:0xf bank_mask:0xf
	v_mov_b32_e32 v11, v10
	v_mov_b32_e32 v130, v10
	s_nop 1
	v_permlane16_swap_b32 v11, v130
	v_add_f32_e32 v10, v11, v130
	v_mov_b32_e32 v11, v10
	v_mov_b32_e32 v130, v10
	s_nop 1
	v_permlane32_swap_b32 v130, v11
	s_and_saveexec_b64 s[18:19], s[4:5]
	s_cbranch_execz .LBB0_841
	v_add_f32_e32 v10, v10, v11
	s_add_i32 s52, s27, 0
	v_mul_f32_e32 v10, 0.5, v10
	v_mov_b32_e32 v11, s52
	ds_write_b32 v11, v10 offset:2060
.LBB0_841:
	s_or_b64 exec, exec, s[18:19]
	s_and_saveexec_b64 s[18:19], s[6:7]
	ds_write_b32 v50, v5 offset:3088
	s_or_b64 exec, exec, s[18:19]
	v_mov_b32_e32 v10, v128
	v_mov_b32_e32 v107, v106
	v_mov_b32_e32 v130, v106
	s_nop 1
	v_permlane32_swap_b32 v107, v130
	v_add_f32_e32 v5, v107, v130
	v_mul_f32_e32 v5, 0x3e000000, v5
	v_mov_b32_e32 v13, s50
	s_waitcnt vmcnt(0)
	v_max_f32_e32 v10, v10, v10
	v_max_f32_e32 v12, v5, v10
	v_add_u32_e32 v10, 0x800, v13
	s_waitcnt lgkmcnt(0)
	ds_read2_b32 v[10:11], v10 offset0:4 offset1:12
	s_waitcnt lgkmcnt(0)
	v_max3_f32 v10, v12, v10, v11
	v_mov_b32_e32 v12, s51
	ds_read_b32 v11, v13 offset:2128
	ds_read_b32 v12, v12 offset:2064
	s_waitcnt lgkmcnt(0)
	v_max3_f32 v10, v10, v11, v12
	v_sub_f32_e32 v11, v103, v10
	v_mul_f32_e32 v11, 0x3fb8aa3b, v11
	v_exp_f32_e32 v11, v11
	s_nop 1
	v_add_f32_dpp v12, v11, v11 quad_perm:[1,0,3,2] row_mask:0xf bank_mask:0xf
	s_nop 1
	v_add_f32_dpp v12, v12, v12 quad_perm:[2,3,0,1] row_mask:0xf bank_mask:0xf
	s_nop 1
	v_add_f32_dpp v12, v12, v12 row_half_mirror row_mask:0xf bank_mask:0xf
	s_nop 1
	v_add_f32_dpp v12, v12, v12 row_mirror row_mask:0xf bank_mask:0xf
	v_mov_b32_e32 v13, v12
	v_mov_b32_e32 v130, v12
	s_nop 1
	v_permlane16_swap_b32 v13, v130
	v_add_f32_e32 v12, v13, v130
	v_mov_b32_e32 v13, v12
	v_mov_b32_e32 v130, v12
	s_nop 1
	v_permlane32_swap_b32 v130, v13
	s_and_saveexec_b64 s[18:19], s[4:5]
	s_cbranch_execz .LBB0_845
	v_add_f32_e32 v12, v12, v13
	s_add_i32 s52, s27, 0
	v_mul_f32_e32 v12, 0.5, v12
	v_mov_b32_e32 v13, s52
	ds_write_b32 v13, v12 offset:2068
.LBB0_845:
	s_or_b64 exec, exec, s[18:19]
	s_and_saveexec_b64 s[18:19], s[6:7]
	ds_write_b32 v50, v11 offset:3616
	s_or_b64 exec, exec, s[18:19]
	v_mov_b32_e32 v4, v3
	v_mov_b32_e32 v130, v3
	s_nop 1
	v_permlane32_swap_b32 v4, v130
	v_add_f32_e32 v3, v4, v130
	v_mov_b32_e32 v4, v129
	v_mov_b32_e32 v11, s50
	v_add_u32_e32 v12, 0x800, v11
	s_waitcnt lgkmcnt(0)
	ds_read2_b32 v[12:13], v12 offset0:6 offset1:14
	v_mul_f32_e32 v3, 0x3e000000, v3
	ds_read_b32 v11, v11 offset:2136
	s_waitcnt vmcnt(0)
	v_max_f32_e32 v4, v4, v4
	v_max_f32_e32 v4, v3, v4
	s_waitcnt lgkmcnt(1)
	v_max3_f32 v4, v4, v12, v13
	v_mov_b32_e32 v12, s51
	ds_read_b32 v12, v12 offset:2072
	s_waitcnt lgkmcnt(0)
	v_max3_f32 v4, v4, v11, v12
	v_sub_f32_e32 v9, v9, v4
	v_mul_f32_e32 v9, 0x3fb8aa3b, v9
	v_exp_f32_e32 v9, v9
	s_nop 1
	v_add_f32_dpp v11, v9, v9 quad_perm:[1,0,3,2] row_mask:0xf bank_mask:0xf
	s_nop 1
	v_add_f32_dpp v11, v11, v11 quad_perm:[2,3,0,1] row_mask:0xf bank_mask:0xf
	s_nop 1
	v_add_f32_dpp v11, v11, v11 row_half_mirror row_mask:0xf bank_mask:0xf
	s_nop 1
	v_add_f32_dpp v11, v11, v11 row_mirror row_mask:0xf bank_mask:0xf
	v_mov_b32_e32 v12, v11
	v_mov_b32_e32 v130, v11
	s_nop 1
	v_permlane16_swap_b32 v12, v130
	v_add_f32_e32 v11, v12, v130
	v_mov_b32_e32 v12, v11
	v_mov_b32_e32 v130, v11
	s_nop 1
	v_permlane32_swap_b32 v130, v12
	s_and_saveexec_b64 s[18:19], s[4:5]
	s_cbranch_execz .LBB0_849
	v_add_f32_e32 v11, v11, v12
	s_add_i32 s52, s27, 0
	v_mul_f32_e32 v11, 0.5, v11
	v_mov_b32_e32 v12, s52
	ds_write_b32 v12, v11 offset:2076
.LBB0_849:
	s_or_b64 exec, exec, s[18:19]
	s_and_saveexec_b64 s[18:19], s[6:7]
	ds_write_b32 v51, v9 offset:2560
	s_or_b64 exec, exec, s[18:19]
	v_mov_b32_e32 v11, s28
	s_waitcnt lgkmcnt(0)
	s_barrier
	ds_read_b128 v[12:15], v11 offset:2560
	ds_read_b128 v[16:19], v11 offset:2576
	ds_read_b128 v[20:23], v11 offset:2592
	ds_read_b128 v[24:27], v11 offset:2608
	v_sub_f32_e32 v7, v7, v8
	s_waitcnt lgkmcnt(3)
	v_fma_f32 v28, v70, v12, 0
	v_fmac_f32_e32 v28, v69, v13
	v_fmac_f32_e32 v28, v68, v14
	v_fmac_f32_e32 v28, v37, v15
	s_waitcnt lgkmcnt(2)
	v_fmac_f32_e32 v28, v78, v16
	v_fmac_f32_e32 v28, v77, v17
	v_fmac_f32_e32 v28, v76, v18
	v_fmac_f32_e32 v28, v75, v19
	s_waitcnt lgkmcnt(1)
	v_fmac_f32_e32 v28, v74, v20
	v_fmac_f32_e32 v28, v73, v21
	v_fmac_f32_e32 v28, v72, v22
	v_fmac_f32_e32 v28, v71, v23
	ds_read_b128 v[12:15], v11 offset:2624
	ds_read_b128 v[16:19], v11 offset:2640
	s_waitcnt lgkmcnt(2)
	v_fmac_f32_e32 v28, v86, v24
	v_fmac_f32_e32 v28, v83, v25
	v_fmac_f32_e32 v28, v84, v26
	v_fmac_f32_e32 v28, v85, v27
	s_waitcnt lgkmcnt(1)
	v_fmac_f32_e32 v28, v79, v12
	v_fmac_f32_e32 v28, v80, v13
	v_fmac_f32_e32 v28, v81, v14
	v_fmac_f32_e32 v28, v82, v15
	ds_read_b128 v[12:15], v11 offset:2656
	s_waitcnt lgkmcnt(1)
	v_fmac_f32_e32 v28, v87, v16
	v_fmac_f32_e32 v28, v94, v17
	v_fmac_f32_e32 v28, v95, v18
	v_fmac_f32_e32 v28, v96, v19
	ds_read_b128 v[16:19], v11 offset:2672
	s_waitcnt lgkmcnt(1)
	v_fmac_f32_e32 v28, v89, v12
	v_fmac_f32_e32 v28, v90, v13
	v_fmac_f32_e32 v28, v91, v14
	v_fmac_f32_e32 v28, v92, v15
	v_mul_f32_e32 v7, 0x3fb8aa3b, v7
	s_waitcnt lgkmcnt(0)
	v_fmac_f32_e32 v28, v93, v16
	v_exp_f32_e32 v9, v7
	v_fmac_f32_e32 v28, v38, v17
	v_fmac_f32_e32 v28, v39, v18
	v_fmac_f32_e32 v28, v88, v19
	v_fma_f32 v7, v97, v9, v28
	v_cndmask_b32_e64 v7, v28, v7, s[8:9]
	ds_write_b32 v52, v7 offset:7168
	ds_read_b128 v[12:15], v11 offset:3088
	ds_read_b128 v[16:19], v11 offset:3104
	ds_read_b128 v[20:23], v11 offset:3120
	ds_read_b128 v[24:27], v11 offset:3136
	v_sub_f32_e32 v2, v2, v6
	s_waitcnt lgkmcnt(3)
	v_fma_f32 v28, v70, v12, 0
	v_fmac_f32_e32 v28, v69, v13
	v_fmac_f32_e32 v28, v68, v14
	v_fmac_f32_e32 v28, v37, v15
	s_waitcnt lgkmcnt(2)
	v_fmac_f32_e32 v28, v78, v16
	v_fmac_f32_e32 v28, v77, v17
	v_fmac_f32_e32 v28, v76, v18
	v_fmac_f32_e32 v28, v75, v19
	s_waitcnt lgkmcnt(1)
	v_fmac_f32_e32 v28, v74, v20
	v_fmac_f32_e32 v28, v73, v21
	v_fmac_f32_e32 v28, v72, v22
	v_fmac_f32_e32 v28, v71, v23
	ds_read_b128 v[12:15], v11 offset:3152
	ds_read_b128 v[16:19], v11 offset:3168
	s_waitcnt lgkmcnt(2)
	v_fmac_f32_e32 v28, v86, v24
	v_fmac_f32_e32 v28, v83, v25
	v_fmac_f32_e32 v28, v84, v26
	v_fmac_f32_e32 v28, v85, v27
	s_waitcnt lgkmcnt(1)
	v_fmac_f32_e32 v28, v79, v12
	v_fmac_f32_e32 v28, v80, v13
	v_fmac_f32_e32 v28, v81, v14
	v_fmac_f32_e32 v28, v82, v15
	ds_read_b128 v[12:15], v11 offset:3184
	s_waitcnt lgkmcnt(1)
	v_fmac_f32_e32 v28, v87, v16
	v_fmac_f32_e32 v28, v94, v17
	v_fmac_f32_e32 v28, v95, v18
	v_fmac_f32_e32 v28, v96, v19
	ds_read_b128 v[16:19], v11 offset:3200
	s_waitcnt lgkmcnt(1)
	v_fmac_f32_e32 v28, v89, v12
	v_fmac_f32_e32 v28, v90, v13
	v_fmac_f32_e32 v28, v91, v14
	v_fmac_f32_e32 v28, v92, v15
	v_mul_f32_e32 v2, 0x3fb8aa3b, v2
	s_waitcnt lgkmcnt(0)
	v_fmac_f32_e32 v28, v93, v16
	v_exp_f32_e32 v7, v2
	v_fmac_f32_e32 v28, v38, v17
	v_fmac_f32_e32 v28, v39, v18
	v_fmac_f32_e32 v28, v88, v19
	v_fma_f32 v2, v97, v7, v28
	v_cndmask_b32_e64 v2, v28, v2, s[8:9]
	ds_write_b32 v52, v2 offset:7424
	ds_read_b128 v[12:15], v11 offset:3616
	ds_read_b128 v[16:19], v11 offset:3632
	ds_read_b128 v[20:23], v11 offset:3648
	ds_read_b128 v[24:27], v11 offset:3664
	v_sub_f32_e32 v5, v5, v10
	s_waitcnt lgkmcnt(3)
	v_fma_f32 v2, v70, v12, 0
	v_fmac_f32_e32 v2, v69, v13
	v_fmac_f32_e32 v2, v68, v14
	v_fmac_f32_e32 v2, v37, v15
	s_waitcnt lgkmcnt(2)
	v_fmac_f32_e32 v2, v78, v16
	v_fmac_f32_e32 v2, v77, v17
	v_fmac_f32_e32 v2, v76, v18
	v_fmac_f32_e32 v2, v75, v19
	s_waitcnt lgkmcnt(1)
	v_fmac_f32_e32 v2, v74, v20
	v_fmac_f32_e32 v2, v73, v21
	v_fmac_f32_e32 v2, v72, v22
	v_fmac_f32_e32 v2, v71, v23
	ds_read_b128 v[12:15], v11 offset:3680
	ds_read_b128 v[16:19], v11 offset:3696
	s_waitcnt lgkmcnt(2)
	v_fmac_f32_e32 v2, v86, v24
	v_fmac_f32_e32 v2, v83, v25
	v_fmac_f32_e32 v2, v84, v26
	v_fmac_f32_e32 v2, v85, v27
	s_waitcnt lgkmcnt(1)
	v_fmac_f32_e32 v2, v79, v12
	v_fmac_f32_e32 v2, v80, v13
	v_fmac_f32_e32 v2, v81, v14
	v_fmac_f32_e32 v2, v82, v15
	ds_read_b128 v[12:15], v11 offset:3712
	s_waitcnt lgkmcnt(1)
	v_fmac_f32_e32 v2, v87, v16
	v_fmac_f32_e32 v2, v94, v17
	v_fmac_f32_e32 v2, v95, v18
	v_fmac_f32_e32 v2, v96, v19
	ds_read_b128 v[16:19], v11 offset:3728
	s_waitcnt lgkmcnt(1)
	v_fmac_f32_e32 v2, v89, v12
	v_fmac_f32_e32 v2, v90, v13
	v_fmac_f32_e32 v2, v91, v14
	v_fmac_f32_e32 v2, v92, v15
	v_mul_f32_e32 v5, 0x3fb8aa3b, v5
	s_waitcnt lgkmcnt(0)
	v_fmac_f32_e32 v2, v93, v16
	v_exp_f32_e32 v11, v5
	v_fmac_f32_e32 v2, v38, v17
	v_fmac_f32_e32 v2, v39, v18
	v_fmac_f32_e32 v2, v88, v19
	v_fma_f32 v5, v97, v11, v2
	v_cndmask_b32_e64 v2, v2, v5, s[8:9]
	ds_write_b32 v52, v2 offset:7680
	v_mov_b32_e32 v2, s29
	ds_read_b128 v[12:15], v2 offset:2560
	ds_read_b128 v[16:19], v2 offset:2576
	ds_read_b128 v[20:23], v2 offset:2592
	ds_read_b128 v[24:27], v2 offset:2608
	s_lshl_b64 s[14:15], s[14:15], 10
	s_cmp_lt_i32 s25, 2
	s_waitcnt lgkmcnt(3)
	v_fma_f32 v28, v70, v12, 0
	v_fmac_f32_e32 v28, v69, v13
	v_fmac_f32_e32 v28, v68, v14
	v_fmac_f32_e32 v28, v37, v15
	s_waitcnt lgkmcnt(2)
	v_fmac_f32_e32 v28, v78, v16
	v_fmac_f32_e32 v28, v77, v17
	v_fmac_f32_e32 v28, v76, v18
	v_fmac_f32_e32 v28, v75, v19
	s_waitcnt lgkmcnt(1)
	v_fmac_f32_e32 v28, v74, v20
	v_fmac_f32_e32 v28, v73, v21
	v_fmac_f32_e32 v28, v72, v22
	v_fmac_f32_e32 v28, v71, v23
	ds_read_b128 v[12:15], v2 offset:2624
	ds_read_b128 v[16:19], v2 offset:2640
	s_waitcnt lgkmcnt(2)
	v_fmac_f32_e32 v28, v86, v24
	v_fmac_f32_e32 v28, v83, v25
	v_fmac_f32_e32 v28, v84, v26
	v_fmac_f32_e32 v28, v85, v27
	s_waitcnt lgkmcnt(1)
	v_fmac_f32_e32 v28, v79, v12
	v_fmac_f32_e32 v28, v80, v13
	v_fmac_f32_e32 v28, v81, v14
	v_fmac_f32_e32 v28, v82, v15
	ds_read_b128 v[12:15], v2 offset:2656
	s_waitcnt lgkmcnt(1)
	v_fmac_f32_e32 v28, v87, v16
	v_fmac_f32_e32 v28, v94, v17
	v_fmac_f32_e32 v28, v95, v18
	v_fmac_f32_e32 v28, v96, v19
	ds_read_b128 v[16:19], v2 offset:2672
	s_waitcnt lgkmcnt(1)
	v_fmac_f32_e32 v28, v89, v12
	v_fmac_f32_e32 v28, v90, v13
	v_fmac_f32_e32 v28, v91, v14
	v_sub_f32_e32 v2, v3, v4
	v_fmac_f32_e32 v28, v92, v15
	v_mul_f32_e32 v2, 0x3fb8aa3b, v2
	s_waitcnt lgkmcnt(0)
	v_fmac_f32_e32 v28, v93, v16
	v_exp_f32_e32 v5, v2
	v_fmac_f32_e32 v28, v38, v17
	v_fmac_f32_e32 v28, v39, v18
	v_fmac_f32_e32 v28, v88, v19
	v_fma_f32 v2, v97, v5, v28
	v_cndmask_b32_e64 v2, v28, v2, s[8:9]
	ds_write_b32 v52, v2 offset:7936
	v_lshl_add_u64 v[2:3], s[14:15], 2, v[34:35]
	s_mov_b64 s[14:15], -1
	s_waitcnt lgkmcnt(0)
	s_barrier
	s_cbranch_scc1 .LBB0_855
	s_cmp_lt_i32 s25, 3
	s_cbranch_scc0 .LBB0_854
	v_mov_b32_e32 v12, v128
	s_waitcnt vmcnt(0)
	v_sub_f32_e32 v10, v12, v10
	v_mul_f32_e32 v10, 0x3fb8aa3b, v10
	v_exp_f32_e32 v13, v10
	v_mov_b32_e32 v10, s31
	v_mov_b32_e32 v12, s34
	ds_read_b32 v10, v10 offset:2052
	ds_read_b32 v12, v12 offset:2052
	s_waitcnt lgkmcnt(0)
	v_add_f32_e32 v15, v10, v12
	v_mov_b32_e32 v10, s35
	v_mov_b32_e32 v12, s36
	ds_read_b32 v10, v10 offset:2052
	ds_read_b32 v12, v12 offset:2052
	s_waitcnt lgkmcnt(0)
	v_add_f32_e32 v17, v10, v12
	ds_read_b32 v10, v60 offset:7168
	ds_read_b32 v12, v61 offset:7168
	ds_read_b32 v14, v62 offset:7168
	ds_read_b32 v16, v63 offset:7168
	s_waitcnt lgkmcnt(2)
	v_pk_add_f32 v[10:11], v[10:11], v[12:13]
	s_waitcnt lgkmcnt(0)
	v_pk_add_f32 v[12:13], v[14:15], v[16:17]
	s_nop 0
	v_pk_add_f32 v[10:11], v[10:11], v[12:13]
	s_nop 0
	v_div_scale_f32 v12, s[14:15], v11, v11, v10
	v_rcp_f32_e32 v13, v12
	s_lshl_b32 s14, s94, 2
	s_mov_b32 s15, s95
	v_fma_f32 v14, -v12, v13, 1.0
	v_fmac_f32_e32 v13, v14, v13
	v_div_scale_f32 v14, vcc, v10, v11, v10
	v_mul_f32_e32 v15, v14, v13
	v_fma_f32 v16, -v12, v15, v14
	v_fmac_f32_e32 v15, v16, v13
	v_fma_f32 v12, -v12, v15, v14
	v_div_fmas_f32 v12, v12, v13, v15
	v_div_fixup_f32 v12, v12, v11, v10
	v_lshl_add_u64 v[10:11], v[2:3], 0, s[14:15]
	global_store_dword v[10:11], v12, off offset:512

.LBB0_855:
	s_andn2_b64 vcc, exec, s[14:15]
	s_cbranch_vccnz .LBB0_860
	s_cmp_eq_u32 s25, 1
	s_mov_b64 s[14:15], -1
	s_cbranch_scc1 .LBB0_858
	v_mov_b32_e32 v10, v126
	s_add_i32 s14, s27, 0
	s_waitcnt vmcnt(0)
	v_sub_f32_e32 v8, v10, v8
	v_mul_f32_e32 v8, 0x3fb8aa3b, v8
	v_exp_f32_e32 v11, v8
	v_mov_b32_e32 v8, s14
	v_mov_b32_e32 v10, s37
	ds_read_b32 v8, v8 offset:2052
	ds_read_b32 v10, v10 offset:2052
	s_waitcnt lgkmcnt(0)
	v_add_f32_e32 v13, v8, v10
	v_mov_b32_e32 v8, s38
	v_mov_b32_e32 v10, s39
	ds_read_b32 v8, v8 offset:2052
	ds_read_b32 v10, v10 offset:2052
	s_waitcnt lgkmcnt(0)
	v_add_f32_e32 v15, v8, v10
	ds_read_b32 v8, v52 offset:7168
	ds_read_b32 v10, v53 offset:7168
	ds_read_b32 v12, v54 offset:7168
	ds_read_b32 v14, v55 offset:7168
	s_waitcnt lgkmcnt(2)
	v_pk_add_f32 v[8:9], v[8:9], v[10:11]
	s_waitcnt lgkmcnt(0)
	v_pk_add_f32 v[10:11], v[12:13], v[14:15]
	s_nop 0
	v_pk_add_f32 v[8:9], v[8:9], v[10:11]
	s_nop 0
	v_div_scale_f32 v10, s[14:15], v9, v9, v8
	v_rcp_f32_e32 v11, v10
	s_lshl_b32 s14, s94, 2
	s_mov_b32 s15, s95
	v_fma_f32 v12, -v10, v11, 1.0
	v_fmac_f32_e32 v11, v12, v11
	v_div_scale_f32 v12, vcc, v8, v9, v8
	v_mul_f32_e32 v13, v12, v11
	v_fma_f32 v14, -v10, v13, v12
	v_fmac_f32_e32 v13, v14, v11
	v_fma_f32 v10, -v10, v13, v12
	v_div_fmas_f32 v10, v10, v11, v13
	v_div_fixup_f32 v10, v10, v9, v8
	v_lshl_add_u64 v[8:9], v[2:3], 0, s[14:15]
	s_mov_b64 s[14:15], 0
	global_store_dword v[8:9], v10, off
.LBB0_858:
	s_andn2_b64 vcc, exec, s[14:15]
	s_cbranch_vccnz .LBB0_860
	v_mov_b32_e32 v8, v127
	s_waitcnt vmcnt(0)
	v_sub_f32_e32 v6, v8, v6
	v_mul_f32_e32 v6, 0x3fb8aa3b, v6
	v_exp_f32_e32 v9, v6
	v_mov_b32_e32 v6, s42
	v_mov_b32_e32 v8, s43
	ds_read_b32 v6, v6 offset:2052
	ds_read_b32 v8, v8 offset:2052
	s_waitcnt lgkmcnt(0)
	v_add_f32_e32 v11, v6, v8
	v_mov_b32_e32 v6, s44
	v_mov_b32_e32 v8, s45
	ds_read_b32 v6, v6 offset:2052
	ds_read_b32 v8, v8 offset:2052
	s_waitcnt lgkmcnt(0)
	v_add_f32_e32 v13, v6, v8
	ds_read_b32 v6, v56 offset:7168
	ds_read_b32 v8, v57 offset:7168
	ds_read_b32 v10, v58 offset:7168
	ds_read_b32 v12, v59 offset:7168
	s_waitcnt lgkmcnt(2)
	v_pk_add_f32 v[6:7], v[6:7], v[8:9]
	s_waitcnt lgkmcnt(0)
	v_pk_add_f32 v[8:9], v[10:11], v[12:13]
	s_nop 0
	v_pk_add_f32 v[6:7], v[6:7], v[8:9]
	s_nop 0
	v_div_scale_f32 v8, s[14:15], v7, v7, v6
	v_rcp_f32_e32 v9, v8
	s_lshl_b32 s14, s94, 2
	s_mov_b32 s15, s95
	v_fma_f32 v10, -v8, v9, 1.0
	v_fmac_f32_e32 v9, v10, v9
	v_div_scale_f32 v10, vcc, v6, v7, v6
	v_mul_f32_e32 v11, v10, v9
	v_fma_f32 v12, -v8, v11, v10
	v_fmac_f32_e32 v11, v12, v9
	v_fma_f32 v8, -v8, v11, v10
	v_div_fmas_f32 v8, v8, v9, v11
	v_div_fixup_f32 v8, v8, v7, v6
	v_lshl_add_u64 v[6:7], v[2:3], 0, s[14:15]
	global_store_dword v[6:7], v8, off offset:256
.LBB0_860:
	s_andn2_b64 vcc, exec, s[8:9]
	s_cbranch_vccnz .LBB0_826
	v_mov_b32_e32 v6, v129
	s_lshl_b32 s94, s94, 2
	v_lshl_add_u64 v[2:3], v[2:3], 0, s[94:95]
	s_waitcnt vmcnt(0)
	v_sub_f32_e32 v4, v6, v4
	v_mul_f32_e32 v4, 0x3fb8aa3b, v4
	v_exp_f32_e32 v7, v4
	v_mov_b32_e32 v4, s46
	v_mov_b32_e32 v6, s47
	ds_read_b32 v4, v4 offset:2052
	ds_read_b32 v6, v6 offset:2052
	s_waitcnt lgkmcnt(0)
	v_add_f32_e32 v9, v4, v6
	v_mov_b32_e32 v4, s48
	v_mov_b32_e32 v6, s49
	ds_read_b32 v4, v4 offset:2052
	ds_read_b32 v6, v6 offset:2052
	s_waitcnt lgkmcnt(0)
	v_add_f32_e32 v11, v4, v6
	ds_read_b32 v4, v64 offset:7168
	ds_read_b32 v6, v65 offset:7168
	ds_read_b32 v8, v66 offset:7168
	ds_read_b32 v10, v67 offset:7168
	s_waitcnt lgkmcnt(2)
	v_pk_add_f32 v[4:5], v[4:5], v[6:7]
	s_waitcnt lgkmcnt(0)
	v_pk_add_f32 v[6:7], v[8:9], v[10:11]
	s_nop 0
	v_pk_add_f32 v[4:5], v[4:5], v[6:7]
	s_nop 0
	v_div_scale_f32 v6, s[14:15], v5, v5, v4
	v_rcp_f32_e32 v7, v6
	s_nop 0
	v_fma_f32 v8, -v6, v7, 1.0
	v_fmac_f32_e32 v7, v8, v7
	v_div_scale_f32 v8, vcc, v4, v5, v4
	v_mul_f32_e32 v9, v8, v7
	v_fma_f32 v10, -v6, v9, v8
	v_fmac_f32_e32 v9, v10, v7
	v_fma_f32 v6, -v6, v9, v8
	v_div_fmas_f32 v6, v6, v7, v9
	v_div_fixup_f32 v4, v6, v5, v4
	global_store_dword v[2:3], v4, off offset:768
	s_branch .LBB0_826
